# v12 + gates tail: four PS1 row scales fetched by one 16B load ahead of the A stream, per-section vmcnt(0) waits (which also waited for store acks) removed
# baseline (speedup 1.0000x reference)
; __device__ __forceinline__ f32x4 mfma16(bf16x8 a, bf16x8 b, f32x4 c) { return __builtin_amdgcn_mfma_f32_16x16x32_bf16(a, b, c, 0, 0, 0); }
; __device__ __forceinline__ float row_rs(const float* ss, int row) { return rsqrtf(ss[row] * (1.f / 1024.f) + EPS); }
; __device__ __forceinline__ void gates_phase(const Args& a) {
;     ...
;     for (int it = gw; it < T / 16; it += NGW) {
;         const int r0 = it * 16; f32x4 acc = {0.f, 0.f, 0.f, 0.f};
;         const bf16_t* ap = XB + (size_t)(r0 + c16) * D + 8 * g; const bf16_t* bp = WG + (size_t)c16 * D + 8 * g;
; #pragma unroll 8
;         for (int kk = 0; kk < 32; ++kk) { const bf16x8 av = *(const bf16x8*)(ap + 32 * kk); const bf16x8 bv = *(const bf16x8*)(bp + 32 * kk); acc = mfma16(av, bv, acc); }
; #pragma unroll
;         for (int j = 0; j < 4; ++j) { const int row = r0 + 4 * g + j; float v = acc[j] * row_rs(PS1, row) + bias;
.LBB0_441:
	v_ashrrev_i32_e32 v13, 31, v12
	v_lshlrev_b64 v[2:3], 11, v[12:13]
	v_lshl_add_u64 v[18:19], v[10:11], 0, v[2:3]
	s_mov_b64 s[4:5], 0
	v_mov_b32_e32 v2, 0
	v_mov_b32_e32 v3, v9
	v_mov_b32_e32 v4, v9
	v_mov_b32_e32 v5, v9
	v_lshl_or_b32 v64, s3, 4, v22
	v_ashrrev_i32_e32 v65, 31, v64
	v_lshl_add_u64 v[64:65], v[64:65], 2, s[34:35]
	global_load_dwordx4 v[60:63], v[64:65], off
	v_add_co_u32_e32 v20, vcc, 0x36a8000, v18
	s_nop 1
	v_addc_co_u32_e32 v21, vcc, 0, v19, vcc
	global_load_dwordx4 v[28:31], v[20:21], off
	global_load_dwordx4 v[32:35], v[20:21], off offset:64
	global_load_dwordx4 v[36:39], v[20:21], off offset:128
	global_load_dwordx4 v[40:43], v[20:21], off offset:192
	global_load_dwordx4 v[44:47], v[20:21], off offset:256
	global_load_dwordx4 v[48:51], v[20:21], off offset:320
	global_load_dwordx4 v[52:55], v[20:21], off offset:384
	global_load_dwordx4 v[56:59], v[20:21], off offset:448
	s_waitcnt vmcnt(7)
	v_mfma_f32_16x16x32_bf16 v[2:5], v[28:31], v[66:69], v[2:5]
	global_load_dwordx4 v[28:31], v[20:21], off offset:512
	s_waitcnt vmcnt(7)
	v_mfma_f32_16x16x32_bf16 v[2:5], v[32:35], v[70:73], v[2:5]
	global_load_dwordx4 v[32:35], v[20:21], off offset:576
	s_waitcnt vmcnt(7)
	v_mfma_f32_16x16x32_bf16 v[2:5], v[36:39], v[74:77], v[2:5]
	global_load_dwordx4 v[36:39], v[20:21], off offset:640
	s_waitcnt vmcnt(7)
	v_mfma_f32_16x16x32_bf16 v[2:5], v[40:43], v[78:81], v[2:5]
	global_load_dwordx4 v[40:43], v[20:21], off offset:704
	s_waitcnt vmcnt(7)
	v_mfma_f32_16x16x32_bf16 v[2:5], v[44:47], v[82:85], v[2:5]
	global_load_dwordx4 v[44:47], v[20:21], off offset:768
	s_waitcnt vmcnt(7)
	v_mfma_f32_16x16x32_bf16 v[2:5], v[48:51], v[86:89], v[2:5]
	global_load_dwordx4 v[48:51], v[20:21], off offset:832
	s_waitcnt vmcnt(7)
	v_mfma_f32_16x16x32_bf16 v[2:5], v[52:55], v[90:93], v[2:5]
	global_load_dwordx4 v[52:55], v[20:21], off offset:896
	s_waitcnt vmcnt(7)
	v_mfma_f32_16x16x32_bf16 v[2:5], v[56:59], v[94:97], v[2:5]
	global_load_dwordx4 v[56:59], v[20:21], off offset:960
	s_waitcnt vmcnt(7)
	v_mfma_f32_16x16x32_bf16 v[2:5], v[28:31], v[100:103], v[2:5]
	global_load_dwordx4 v[28:31], v[20:21], off offset:1024
	s_waitcnt vmcnt(7)
	v_mfma_f32_16x16x32_bf16 v[2:5], v[32:35], v[104:107], v[2:5]
	global_load_dwordx4 v[32:35], v[20:21], off offset:1088
	s_waitcnt vmcnt(7)
	v_mfma_f32_16x16x32_bf16 v[2:5], v[36:39], v[108:111], v[2:5]
	global_load_dwordx4 v[36:39], v[20:21], off offset:1152
	s_waitcnt vmcnt(7)
	v_mfma_f32_16x16x32_bf16 v[2:5], v[40:43], v[112:115], v[2:5]
	global_load_dwordx4 v[40:43], v[20:21], off offset:1216
	s_waitcnt vmcnt(7)
	v_mfma_f32_16x16x32_bf16 v[2:5], v[44:47], v[116:119], v[2:5]
	global_load_dwordx4 v[44:47], v[20:21], off offset:1280
	s_waitcnt vmcnt(7)
	v_mfma_f32_16x16x32_bf16 v[2:5], v[48:51], v[120:123], v[2:5]
	global_load_dwordx4 v[48:51], v[20:21], off offset:1344
	s_waitcnt vmcnt(7)
	v_mfma_f32_16x16x32_bf16 v[2:5], v[52:55], v[124:127], v[2:5]
	global_load_dwordx4 v[52:55], v[20:21], off offset:1408
	s_waitcnt vmcnt(7)
	v_mfma_f32_16x16x32_bf16 v[2:5], v[56:59], v[142:145], v[2:5]
	global_load_dwordx4 v[56:59], v[20:21], off offset:1472
	s_waitcnt vmcnt(7)
	v_mfma_f32_16x16x32_bf16 v[2:5], v[28:31], v[146:149], v[2:5]
	global_load_dwordx4 v[28:31], v[20:21], off offset:1536
	s_waitcnt vmcnt(7)
	v_mfma_f32_16x16x32_bf16 v[2:5], v[32:35], v[150:153], v[2:5]
	global_load_dwordx4 v[32:35], v[20:21], off offset:1600
	s_waitcnt vmcnt(7)
	v_mfma_f32_16x16x32_bf16 v[2:5], v[36:39], v[154:157], v[2:5]
	global_load_dwordx4 v[36:39], v[20:21], off offset:1664
	s_waitcnt vmcnt(7)
	v_mfma_f32_16x16x32_bf16 v[2:5], v[40:43], v[158:161], v[2:5]
	global_load_dwordx4 v[40:43], v[20:21], off offset:1728
	s_waitcnt vmcnt(7)
	v_mfma_f32_16x16x32_bf16 v[2:5], v[44:47], v[162:165], v[2:5]
	global_load_dwordx4 v[44:47], v[20:21], off offset:1792
	s_waitcnt vmcnt(7)
	v_mfma_f32_16x16x32_bf16 v[2:5], v[48:51], v[166:169], v[2:5]
	global_load_dwordx4 v[48:51], v[20:21], off offset:1856
	s_waitcnt vmcnt(7)
	v_mfma_f32_16x16x32_bf16 v[2:5], v[52:55], v[170:173], v[2:5]
	global_load_dwordx4 v[52:55], v[20:21], off offset:1920
	s_waitcnt vmcnt(7)
	v_mfma_f32_16x16x32_bf16 v[2:5], v[56:59], v[184:187], v[2:5]
	global_load_dwordx4 v[56:59], v[20:21], off offset:1984
	s_waitcnt vmcnt(7)
	v_mfma_f32_16x16x32_bf16 v[2:5], v[28:31], v[188:191], v[2:5]
	s_waitcnt vmcnt(6)
	v_mfma_f32_16x16x32_bf16 v[2:5], v[32:35], v[198:201], v[2:5]
	s_waitcnt vmcnt(5)
	v_mfma_f32_16x16x32_bf16 v[2:5], v[36:39], v[202:205], v[2:5]
	s_waitcnt vmcnt(4)
	v_mfma_f32_16x16x32_bf16 v[2:5], v[40:43], v[206:209], v[2:5]
	s_waitcnt vmcnt(3)
	v_mfma_f32_16x16x32_bf16 v[2:5], v[44:47], v[210:213], v[2:5]
	s_waitcnt vmcnt(2)
	v_mfma_f32_16x16x32_bf16 v[2:5], v[48:51], v[218:221], v[2:5]
	s_waitcnt vmcnt(1)
	v_mfma_f32_16x16x32_bf16 v[2:5], v[52:55], v[222:225], v[2:5]
	s_waitcnt vmcnt(0)
	v_mfma_f32_16x16x32_bf16 v[2:5], v[56:59], v[226:229], v[2:5]
	v_lshl_or_b32 v18, s3, 4, v22
	v_ashrrev_i32_e32 v19, 31, v18
	v_lshl_add_u64 v[20:21], v[18:19], 2, s[34:35]
	v_mov_b32_e32 v13, v60
	s_waitcnt vmcnt(0)
	v_fmamk_f32 v13, v13, 0x3a800000, v8
	v_mul_f32_e32 v17, 0x4b800000, v13
	v_cmp_gt_f32_e32 vcc, s8, v13
	s_nop 1
	v_cndmask_b32_e32 v13, v13, v17, vcc
	v_rsq_f32_e32 v13, v13
	s_nop 0
	v_mul_f32_e32 v17, 0x45800000, v13
	v_cndmask_b32_e32 v13, v13, v17, vcc
	v_fma_f32 v2, v2, v13, v1
	s_and_saveexec_b64 s[4:5], s[0:1]
	s_cbranch_execz .LBB0_445
; __device__ __forceinline__ void gates_phase(const Args& a) {
;     ...
;             if (isf) v = fminf(v, 0.f) - log1pf(__expf(-fabsf(v)));
	v_mul_f32_e64 v13, |v2|, s9
	v_exp_f32_e32 v13, v13
	v_max_f32_e32 v2, v2, v2
	v_min_f32_e32 v2, 0, v2
	v_add_f32_e32 v17, 1.0, v13
	v_add_f32_e32 v20, -1.0, v17
	v_sub_f32_e32 v21, v20, v17
	v_sub_f32_e32 v20, v13, v20
	v_add_f32_e32 v21, 1.0, v21
	v_add_f32_e32 v27, v20, v21
	v_frexp_mant_f32_e32 v28, v17
	v_cvt_f64_f32_e32 v[20:21], v17
	v_frexp_exp_i32_f64_e32 v20, v[20:21]
	v_cmp_gt_f32_e32 vcc, s10, v28
	s_nop 1
	v_subbrev_co_u32_e32 v34, vcc, 0, v20, vcc
	v_sub_u32_e32 v20, 0, v34
	v_ldexp_f32 v17, v17, v20
	v_ldexp_f32 v20, v27, v20
	v_add_f32_e32 v27, -1.0, v17
	v_add_f32_e32 v21, 1.0, v27
	v_sub_f32_e32 v21, v17, v21
	v_add_f32_e32 v28, v20, v21
	v_add_f32_e32 v21, 1.0, v17
	v_add_f32_e32 v29, -1.0, v21
	v_sub_f32_e32 v17, v17, v29
	v_add_f32_e32 v17, v20, v17
	v_add_f32_e32 v35, v21, v17
	v_rcp_f32_e32 v36, v35
	v_sub_f32_e32 v20, v35, v21
	v_add_f32_e32 v21, v27, v28
	v_sub_f32_e32 v17, v17, v20
	v_sub_f32_e32 v20, v21, v27
	v_mul_f32_e32 v37, v21, v36
	v_sub_f32_e32 v27, v28, v20
	v_mul_f32_e32 v28, v35, v37
	v_fma_f32 v30, v37, v35, -v28
	v_fmac_f32_e32 v30, v37, v17
	v_add_f32_e32 v20, v28, v30
	v_sub_f32_e32 v29, v21, v20
	v_pk_add_f32 v[32:33], v[20:21], v[28:29] neg_lo:[0,1] neg_hi:[0,1]
	v_mov_b32_e32 v31, v20
	v_pk_add_f32 v[20:21], v[32:33], v[30:31] neg_lo:[0,1] neg_hi:[0,1]
	v_cmp_neq_f32_e32 vcc, s12, v13
	v_add_f32_e32 v21, v27, v21
	v_add_f32_e32 v20, v20, v21
	v_add_f32_e32 v21, v29, v20
	v_mul_f32_e32 v27, v36, v21
	v_mul_f32_e32 v28, v35, v27
	v_fma_f32 v30, v27, v35, -v28
	v_fmac_f32_e32 v30, v27, v17
	v_sub_f32_e32 v17, v29, v21
	v_add_f32_e32 v17, v20, v17
	v_add_f32_e32 v20, v28, v30
	v_sub_f32_e32 v29, v21, v20
	v_pk_add_f32 v[32:33], v[20:21], v[28:29] neg_lo:[0,1] neg_hi:[0,1]
	v_mov_b32_e32 v31, v20
	v_pk_add_f32 v[20:21], v[32:33], v[30:31] neg_lo:[0,1] neg_hi:[0,1]
	s_nop 0
	v_add_f32_e32 v17, v17, v21
	v_add_f32_e32 v17, v20, v17
	v_add_f32_e32 v21, v37, v27
	v_add_f32_e32 v17, v29, v17
	v_sub_f32_e32 v20, v21, v37
	v_mul_f32_e32 v17, v36, v17
	v_sub_f32_e32 v20, v27, v20
	v_add_f32_e32 v27, v20, v17
	v_add_f32_e32 v28, v21, v27
	v_cvt_f32_i32_e32 v20, v34
	v_mul_f32_e32 v30, v28, v28
	v_sub_f32_e32 v21, v28, v21
	v_fmamk_f32 v17, v30, 0x3e9b6dac, v23
	v_sub_f32_e32 v21, v27, v21
	v_fmaak_f32 v17, v30, v17, 0x3f2aaada
	v_ldexp_f32 v27, v21, 1
	v_mul_f32_e32 v21, v28, v30
	v_pk_mul_f32 v[30:31], v[20:21], v[16:17]
	v_ldexp_f32 v29, v28, 1
	v_fma_f32 v28, v20, s11, -v30
	v_fmac_f32_e32 v28, 0xb102e308, v20
	v_pk_add_f32 v[20:21], v[30:31], v[28:29]
	v_mov_b32_e32 v32, v30
	v_sub_f32_e32 v17, v21, v29
	v_sub_f32_e32 v17, v31, v17
	v_add_f32_e32 v33, v27, v17
	v_pk_add_f32 v[30:31], v[20:21], v[30:31] neg_lo:[0,1] neg_hi:[0,1]
	v_pk_add_f32 v[34:35], v[20:21], v[32:33]
	v_mov_b32_e32 v29, v20
	v_mov_b32_e32 v31, v35
	v_pk_add_f32 v[36:37], v[28:29], v[30:31] neg_lo:[0,1] neg_hi:[0,1]
	v_pk_add_f32 v[28:29], v[28:29], v[30:31]
	v_mov_b32_e32 v32, v33
	v_pk_add_f32 v[30:31], v[28:29], v[20:21] op_sel:[1,0] op_sel_hi:[0,1] neg_lo:[0,1] neg_hi:[0,1]
	v_pk_add_f32 v[38:39], v[34:35], v[30:31] op_sel_hi:[1,0] neg_lo:[0,1] neg_hi:[0,1]
	v_mov_b32_e32 v34, v35
	v_mov_b32_e32 v35, v29
	v_pk_mov_b32 v[30:31], v[20:21], v[30:31] op_sel:[1,0]
	v_mov_b32_e32 v33, v20
	v_pk_add_f32 v[30:31], v[34:35], v[30:31] neg_lo:[0,1] neg_hi:[0,1]
	v_mov_b32_e32 v38, v36
	v_pk_add_f32 v[20:21], v[32:33], v[30:31] neg_lo:[0,1] neg_hi:[0,1]
	v_mov_b32_e32 v37, v29
	v_pk_add_f32 v[30:31], v[38:39], v[20:21]
	s_nop 0
	v_pk_add_f32 v[32:33], v[30:31], v[30:31] op_sel:[0,1] op_sel_hi:[1,0]
	s_nop 0
	v_pk_add_f32 v[28:29], v[28:29], v[32:33] op_sel:[1,0] op_sel_hi:[0,1]
	v_mov_b32_e32 v31, v28
	v_pk_add_f32 v[34:35], v[30:31], v[36:37] neg_lo:[0,1] neg_hi:[0,1]
	v_mov_b32_e32 v21, v32
	v_sub_f32_e32 v17, v30, v34
	v_pk_add_f32 v[20:21], v[20:21], v[34:35] neg_lo:[0,1] neg_hi:[0,1]
	v_sub_f32_e32 v17, v36, v17
	v_add_f32_e32 v17, v20, v17
	v_add_f32_e32 v17, v17, v21
	v_add_f32_e32 v17, v28, v17
	v_cndmask_b32_e32 v17, v24, v17, vcc
	v_cmp_ngt_f32_e32 vcc, -1.0, v13
	s_nop 1
	v_cndmask_b32_e32 v17, v25, v17, vcc
	v_cmp_neq_f32_e32 vcc, -1.0, v13
	s_nop 1
	v_cndmask_b32_e32 v17, v26, v17, vcc
	v_cmp_lt_f32_e64 vcc, |v13|, s13
	s_nop 1
	v_cndmask_b32_e32 v13, v17, v13, vcc
	v_sub_f32_e32 v2, v2, v13
; __device__ __forceinline__ float row_rs(const float* ss, int row) { return rsqrtf(ss[row] * (1.f / 1024.f) + EPS); }
; __device__ __forceinline__ void gates_phase(const Args& a) {
;     ...
;         for (int j = 0; j < 4; ++j) { const int row = r0 + 4 * g + j; float v = acc[j] * row_rs(PS1, row) + bias;
;             if (isf) v = fminf(v, 0.f) - log1pf(__expf(-fabsf(v)));
;             GATES[(size_t)row * 16 + c16] = v; }
.LBB0_445:
	s_or_b64 exec, exec, s[4:5]
	v_lshlrev_b64 v[20:21], 6, v[18:19]
	v_lshl_add_u64 v[20:21], v[6:7], 0, v[20:21]
	global_store_dword v[20:21], v2, off
	v_or_b32_e32 v20, 1, v18
	v_ashrrev_i32_e32 v21, 31, v20
	v_lshl_add_u64 v[28:29], v[20:21], 2, s[34:35]
	v_mov_b32_e32 v2, v61
	v_fmamk_f32 v2, v2, 0x3a800000, v8
	v_mul_f32_e32 v13, 0x4b800000, v2
	v_cmp_gt_f32_e32 vcc, s8, v2
	s_nop 1
	v_cndmask_b32_e32 v2, v2, v13, vcc
	v_rsq_f32_e32 v2, v2
	s_nop 0
	v_mul_f32_e32 v13, 0x45800000, v2
	v_cndmask_b32_e32 v2, v2, v13, vcc
	v_fma_f32 v2, v3, v2, v1
	s_and_saveexec_b64 s[4:5], s[0:1]
	s_cbranch_execz .LBB0_447
	v_mul_f32_e64 v3, |v2|, s9
	v_exp_f32_e32 v13, v3
	v_max_f32_e32 v2, v2, v2
	v_min_f32_e32 v19, 0, v2
	v_add_f32_e32 v17, 1.0, v13
	v_add_f32_e32 v2, -1.0, v17
	v_sub_f32_e32 v3, v2, v17
	v_sub_f32_e32 v2, v13, v2
	v_add_f32_e32 v3, 1.0, v3
	v_add_f32_e32 v27, v2, v3
	v_frexp_mant_f32_e32 v28, v17
	v_cvt_f64_f32_e32 v[2:3], v17
	v_frexp_exp_i32_f64_e32 v2, v[2:3]
	v_cmp_gt_f32_e32 vcc, s10, v28
	s_nop 1
	v_subbrev_co_u32_e32 v34, vcc, 0, v2, vcc
	v_sub_u32_e32 v2, 0, v34
	v_ldexp_f32 v3, v17, v2
	v_add_f32_e32 v17, -1.0, v3
	v_add_f32_e32 v28, 1.0, v3
	v_ldexp_f32 v2, v27, v2
	v_add_f32_e32 v27, 1.0, v17
	v_add_f32_e32 v29, -1.0, v28
	v_sub_f32_e32 v27, v3, v27
	v_sub_f32_e32 v3, v3, v29
	v_add_f32_e32 v27, v2, v27
	v_add_f32_e32 v2, v2, v3
	v_add_f32_e32 v35, v28, v2
	v_rcp_f32_e32 v37, v35
	v_sub_f32_e32 v3, v35, v28
	v_sub_f32_e32 v36, v2, v3
	v_add_f32_e32 v3, v17, v27
	v_sub_f32_e32 v2, v3, v17
	v_sub_f32_e32 v17, v27, v2
	v_mul_f32_e32 v27, v3, v37
	v_mul_f32_e32 v28, v35, v27
	v_fma_f32 v30, v27, v35, -v28
	v_fmac_f32_e32 v30, v27, v36
	v_add_f32_e32 v2, v28, v30
	v_sub_f32_e32 v29, v3, v2
	v_pk_add_f32 v[32:33], v[2:3], v[28:29] neg_lo:[0,1] neg_hi:[0,1]
	v_mov_b32_e32 v31, v2
	v_pk_add_f32 v[2:3], v[32:33], v[30:31] neg_lo:[0,1] neg_hi:[0,1]
	v_cmp_neq_f32_e32 vcc, s12, v13
	v_add_f32_e32 v3, v17, v3
	v_add_f32_e32 v2, v2, v3
	v_add_f32_e32 v3, v29, v2
	v_mul_f32_e32 v17, v37, v3
	v_mul_f32_e32 v28, v35, v17
	v_fma_f32 v30, v17, v35, -v28
	v_fmac_f32_e32 v30, v17, v36
	v_sub_f32_e32 v29, v29, v3
	v_add_f32_e32 v35, v2, v29
	v_add_f32_e32 v2, v28, v30
	v_sub_f32_e32 v29, v3, v2
	v_pk_add_f32 v[32:33], v[2:3], v[28:29] neg_lo:[0,1] neg_hi:[0,1]
	v_mov_b32_e32 v31, v2
	v_pk_add_f32 v[2:3], v[32:33], v[30:31] neg_lo:[0,1] neg_hi:[0,1]
	s_nop 0
	v_add_f32_e32 v3, v35, v3
	v_add_f32_e32 v2, v2, v3
	v_add_f32_e32 v3, v27, v17
	v_add_f32_e32 v2, v29, v2
	v_sub_f32_e32 v27, v3, v27
	v_mul_f32_e32 v2, v37, v2
	v_sub_f32_e32 v17, v17, v27
	v_add_f32_e32 v27, v17, v2
	v_add_f32_e32 v28, v3, v27
	v_mul_f32_e32 v30, v28, v28
	v_fmamk_f32 v2, v30, 0x3e9b6dac, v23
	v_fmaak_f32 v17, v30, v2, 0x3f2aaada
	v_cvt_f32_i32_e32 v2, v34
	v_sub_f32_e32 v3, v28, v3
	v_sub_f32_e32 v3, v27, v3
	v_ldexp_f32 v27, v3, 1
	v_mul_f32_e32 v3, v28, v30
	v_pk_mul_f32 v[30:31], v[2:3], v[16:17]
	v_ldexp_f32 v29, v28, 1
	v_fma_f32 v28, v2, s11, -v30
	v_fmac_f32_e32 v28, 0xb102e308, v2
	v_pk_add_f32 v[2:3], v[30:31], v[28:29]
	v_mov_b32_e32 v32, v30
	v_sub_f32_e32 v17, v3, v29
	v_sub_f32_e32 v17, v31, v17
	v_add_f32_e32 v33, v27, v17
	v_pk_add_f32 v[30:31], v[2:3], v[30:31] neg_lo:[0,1] neg_hi:[0,1]
	v_pk_add_f32 v[34:35], v[2:3], v[32:33]
	v_mov_b32_e32 v29, v2
	v_mov_b32_e32 v31, v35
	v_pk_add_f32 v[36:37], v[28:29], v[30:31] neg_lo:[0,1] neg_hi:[0,1]
	v_pk_add_f32 v[28:29], v[28:29], v[30:31]
	v_mov_b32_e32 v32, v33
	v_pk_add_f32 v[30:31], v[28:29], v[2:3] op_sel:[1,0] op_sel_hi:[0,1] neg_lo:[0,1] neg_hi:[0,1]
	v_pk_add_f32 v[38:39], v[34:35], v[30:31] op_sel_hi:[1,0] neg_lo:[0,1] neg_hi:[0,1]
	v_mov_b32_e32 v34, v35
	v_mov_b32_e32 v35, v29
	v_pk_mov_b32 v[30:31], v[2:3], v[30:31] op_sel:[1,0]
	v_mov_b32_e32 v33, v2
	v_pk_add_f32 v[30:31], v[34:35], v[30:31] neg_lo:[0,1] neg_hi:[0,1]
	v_mov_b32_e32 v38, v36
	v_pk_add_f32 v[2:3], v[32:33], v[30:31] neg_lo:[0,1] neg_hi:[0,1]
	v_mov_b32_e32 v37, v29
	v_pk_add_f32 v[30:31], v[38:39], v[2:3]
	s_nop 0
	v_pk_add_f32 v[32:33], v[30:31], v[30:31] op_sel:[0,1] op_sel_hi:[1,0]
	s_nop 0
	v_pk_add_f32 v[28:29], v[28:29], v[32:33] op_sel:[1,0] op_sel_hi:[0,1]
	v_mov_b32_e32 v31, v28
	v_pk_add_f32 v[34:35], v[30:31], v[36:37] neg_lo:[0,1] neg_hi:[0,1]
	v_mov_b32_e32 v3, v32
	v_sub_f32_e32 v17, v30, v34
	v_pk_add_f32 v[2:3], v[2:3], v[34:35] neg_lo:[0,1] neg_hi:[0,1]
	v_sub_f32_e32 v17, v36, v17
	v_add_f32_e32 v2, v2, v17
	v_add_f32_e32 v2, v2, v3
	v_add_f32_e32 v2, v28, v2
	v_cndmask_b32_e32 v2, v24, v2, vcc
	v_cmp_ngt_f32_e32 vcc, -1.0, v13
	s_nop 1
	v_cndmask_b32_e32 v2, v25, v2, vcc
	v_cmp_neq_f32_e32 vcc, -1.0, v13
	s_nop 1
	v_cndmask_b32_e32 v2, v26, v2, vcc
	v_cmp_lt_f32_e64 vcc, |v13|, s13
	s_nop 1
	v_cndmask_b32_e32 v2, v2, v13, vcc
	v_sub_f32_e32 v2, v19, v2
; __device__ __forceinline__ float row_rs(const float* ss, int row) { return rsqrtf(ss[row] * (1.f / 1024.f) + EPS); }
; __device__ __forceinline__ void gates_phase(const Args& a) {
;     ...
;         for (int j = 0; j < 4; ++j) { const int row = r0 + 4 * g + j; float v = acc[j] * row_rs(PS1, row) + bias;
;             if (isf) v = fminf(v, 0.f) - log1pf(__expf(-fabsf(v)));
;             GATES[(size_t)row * 16 + c16] = v; }
.LBB0_447:
	s_or_b64 exec, exec, s[4:5]
	v_lshlrev_b64 v[20:21], 6, v[20:21]
	v_lshl_add_u64 v[20:21], v[6:7], 0, v[20:21]
	global_store_dword v[20:21], v2, off
	v_or_b32_e32 v2, 2, v18
	v_ashrrev_i32_e32 v3, 31, v2
	v_lshl_add_u64 v[20:21], v[2:3], 2, s[34:35]
	v_mov_b32_e32 v13, v62
	v_fmamk_f32 v13, v13, 0x3a800000, v8
	v_mul_f32_e32 v17, 0x4b800000, v13
	v_cmp_gt_f32_e32 vcc, s8, v13
	s_nop 1
	v_cndmask_b32_e32 v13, v13, v17, vcc
	v_rsq_f32_e32 v13, v13
	s_nop 0
	v_mul_f32_e32 v17, 0x45800000, v13
	v_cndmask_b32_e32 v13, v13, v17, vcc
	v_fma_f32 v4, v4, v13, v1
	s_and_saveexec_b64 s[4:5], s[0:1]
	s_cbranch_execz .LBB0_449
	v_mul_f32_e64 v13, |v4|, s9
	v_exp_f32_e32 v13, v13
	v_max_f32_e32 v4, v4, v4
	v_min_f32_e32 v4, 0, v4
	v_add_f32_e32 v17, 1.0, v13
	v_add_f32_e32 v19, -1.0, v17
	v_sub_f32_e32 v20, v19, v17
	v_sub_f32_e32 v19, v13, v19
	v_add_f32_e32 v20, 1.0, v20
	v_add_f32_e32 v19, v19, v20
	v_frexp_mant_f32_e32 v27, v17
	v_cvt_f64_f32_e32 v[20:21], v17
	v_frexp_exp_i32_f64_e32 v20, v[20:21]
	v_cmp_gt_f32_e32 vcc, s10, v27
	s_nop 1
	v_subbrev_co_u32_e32 v27, vcc, 0, v20, vcc
	v_sub_u32_e32 v20, 0, v27
	v_ldexp_f32 v17, v17, v20
	v_ldexp_f32 v19, v19, v20
	v_add_f32_e32 v20, -1.0, v17
	v_add_f32_e32 v21, 1.0, v20
	v_sub_f32_e32 v21, v17, v21
	v_add_f32_e32 v28, v19, v21
	v_add_f32_e32 v21, 1.0, v17
	v_add_f32_e32 v29, -1.0, v21
	v_sub_f32_e32 v17, v17, v29
	v_add_f32_e32 v17, v19, v17
	v_add_f32_e32 v19, v21, v17
	v_rcp_f32_e32 v34, v19
	v_sub_f32_e32 v21, v19, v21
	v_sub_f32_e32 v17, v17, v21
	v_add_f32_e32 v21, v20, v28
	v_sub_f32_e32 v20, v21, v20
	v_mul_f32_e32 v36, v21, v34
	v_sub_f32_e32 v35, v28, v20
	v_mul_f32_e32 v28, v19, v36
	v_fma_f32 v30, v36, v19, -v28
	v_fmac_f32_e32 v30, v36, v17
	v_add_f32_e32 v20, v28, v30
	v_sub_f32_e32 v29, v21, v20
	v_pk_add_f32 v[32:33], v[20:21], v[28:29] neg_lo:[0,1] neg_hi:[0,1]
	v_mov_b32_e32 v31, v20
	v_pk_add_f32 v[20:21], v[32:33], v[30:31] neg_lo:[0,1] neg_hi:[0,1]
	v_cmp_neq_f32_e32 vcc, s12, v13
	v_add_f32_e32 v21, v35, v21
	v_add_f32_e32 v20, v20, v21
	v_add_f32_e32 v21, v29, v20
	v_mul_f32_e32 v35, v34, v21
	v_mul_f32_e32 v28, v19, v35
	v_fma_f32 v30, v35, v19, -v28
	v_fmac_f32_e32 v30, v35, v17
	v_sub_f32_e32 v17, v29, v21
	v_add_f32_e32 v17, v20, v17
	v_add_f32_e32 v20, v28, v30
	v_sub_f32_e32 v29, v21, v20
	v_pk_add_f32 v[32:33], v[20:21], v[28:29] neg_lo:[0,1] neg_hi:[0,1]
	v_mov_b32_e32 v31, v20
	v_pk_add_f32 v[20:21], v[32:33], v[30:31] neg_lo:[0,1] neg_hi:[0,1]
	v_add_f32_e32 v19, v36, v35
	v_add_f32_e32 v17, v17, v21
	v_add_f32_e32 v17, v20, v17
	v_add_f32_e32 v17, v29, v17
	v_sub_f32_e32 v20, v19, v36
	v_mul_f32_e32 v17, v34, v17
	v_sub_f32_e32 v20, v35, v20
	v_add_f32_e32 v21, v20, v17
	v_add_f32_e32 v28, v19, v21
	v_cvt_f32_i32_e32 v20, v27
	v_mul_f32_e32 v30, v28, v28
	v_fmamk_f32 v17, v30, 0x3e9b6dac, v23
	v_sub_f32_e32 v19, v28, v19
	v_fmaak_f32 v17, v30, v17, 0x3f2aaada
	v_sub_f32_e32 v19, v21, v19
	v_mul_f32_e32 v21, v28, v30
	v_pk_mul_f32 v[30:31], v[20:21], v[16:17]
	v_ldexp_f32 v29, v28, 1
	v_fma_f32 v28, v20, s11, -v30
	v_fmac_f32_e32 v28, 0xb102e308, v20
	v_pk_add_f32 v[20:21], v[30:31], v[28:29]
	v_ldexp_f32 v19, v19, 1
	v_sub_f32_e32 v17, v21, v29
	v_sub_f32_e32 v17, v31, v17
	v_add_f32_e32 v33, v19, v17
	v_mov_b32_e32 v32, v30
	v_pk_add_f32 v[30:31], v[20:21], v[30:31] neg_lo:[0,1] neg_hi:[0,1]
	v_pk_add_f32 v[34:35], v[20:21], v[32:33]
	v_mov_b32_e32 v29, v20
	v_mov_b32_e32 v31, v35
	v_pk_add_f32 v[36:37], v[28:29], v[30:31] neg_lo:[0,1] neg_hi:[0,1]
	v_pk_add_f32 v[28:29], v[28:29], v[30:31]
	v_mov_b32_e32 v32, v33
	v_pk_add_f32 v[30:31], v[28:29], v[20:21] op_sel:[1,0] op_sel_hi:[0,1] neg_lo:[0,1] neg_hi:[0,1]
	v_pk_add_f32 v[38:39], v[34:35], v[30:31] op_sel_hi:[1,0] neg_lo:[0,1] neg_hi:[0,1]
	v_mov_b32_e32 v34, v35
	v_mov_b32_e32 v35, v29
	v_pk_mov_b32 v[30:31], v[20:21], v[30:31] op_sel:[1,0]
	v_mov_b32_e32 v33, v20
	v_pk_add_f32 v[30:31], v[34:35], v[30:31] neg_lo:[0,1] neg_hi:[0,1]
	v_mov_b32_e32 v38, v36
	v_pk_add_f32 v[20:21], v[32:33], v[30:31] neg_lo:[0,1] neg_hi:[0,1]
	v_mov_b32_e32 v37, v29
	v_pk_add_f32 v[30:31], v[38:39], v[20:21]
	s_nop 0
	v_pk_add_f32 v[32:33], v[30:31], v[30:31] op_sel:[0,1] op_sel_hi:[1,0]
	s_nop 0
	v_pk_add_f32 v[28:29], v[28:29], v[32:33] op_sel:[1,0] op_sel_hi:[0,1]
	v_mov_b32_e32 v31, v28
	v_pk_add_f32 v[34:35], v[30:31], v[36:37] neg_lo:[0,1] neg_hi:[0,1]
	v_mov_b32_e32 v21, v32
	v_sub_f32_e32 v17, v30, v34
	v_pk_add_f32 v[20:21], v[20:21], v[34:35] neg_lo:[0,1] neg_hi:[0,1]
	v_sub_f32_e32 v17, v36, v17
	v_add_f32_e32 v17, v20, v17
	v_add_f32_e32 v17, v17, v21
	v_add_f32_e32 v17, v28, v17
	v_cndmask_b32_e32 v17, v24, v17, vcc
	v_cmp_ngt_f32_e32 vcc, -1.0, v13
	s_nop 1
	v_cndmask_b32_e32 v17, v25, v17, vcc
	v_cmp_neq_f32_e32 vcc, -1.0, v13
	s_nop 1
	v_cndmask_b32_e32 v17, v26, v17, vcc
	v_cmp_lt_f32_e64 vcc, |v13|, s13
	s_nop 1
	v_cndmask_b32_e32 v13, v17, v13, vcc
	v_sub_f32_e32 v4, v4, v13
; __device__ __forceinline__ float row_rs(const float* ss, int row) { return rsqrtf(ss[row] * (1.f / 1024.f) + EPS); }
; __device__ __forceinline__ void gates_phase(const Args& a) {
;     ...
;     for (int it = gw; it < T / 16; it += NGW) {
;     ...
;         for (int j = 0; j < 4; ++j) { const int row = r0 + 4 * g + j; float v = acc[j] * row_rs(PS1, row) + bias;
;             if (isf) v = fminf(v, 0.f) - log1pf(__expf(-fabsf(v)));
;             GATES[(size_t)row * 16 + c16] = v; }
.LBB0_449:
	s_or_b64 exec, exec, s[4:5]
	v_lshlrev_b64 v[2:3], 6, v[2:3]
	v_lshl_add_u64 v[2:3], v[6:7], 0, v[2:3]
	global_store_dword v[2:3], v4, off
	v_or_b32_e32 v2, 3, v18
	v_ashrrev_i32_e32 v3, 31, v2
	v_lshl_add_u64 v[18:19], v[2:3], 2, s[34:35]
	v_mov_b32_e32 v4, v63
	v_fmamk_f32 v4, v4, 0x3a800000, v8
	v_mul_f32_e32 v13, 0x4b800000, v4
	v_cmp_gt_f32_e32 vcc, s8, v4
	s_nop 1
	v_cndmask_b32_e32 v4, v4, v13, vcc
	v_rsq_f32_e32 v4, v4
	s_nop 0
	v_mul_f32_e32 v13, 0x45800000, v4
	v_cndmask_b32_e32 v4, v4, v13, vcc
	v_fma_f32 v4, v5, v4, v1
	s_and_saveexec_b64 s[4:5], s[0:1]
	s_cbranch_execz .LBB0_440
	v_mul_f32_e64 v5, |v4|, s9
	v_exp_f32_e32 v13, v5
	v_max_f32_e32 v4, v4, v4
	v_min_f32_e32 v27, 0, v4
	v_add_f32_e32 v17, 1.0, v13
	v_add_f32_e32 v4, -1.0, v17
	v_sub_f32_e32 v5, v4, v17
	v_sub_f32_e32 v4, v13, v4
	v_add_f32_e32 v5, 1.0, v5
	v_add_f32_e32 v18, v4, v5
	v_frexp_mant_f32_e32 v19, v17
	v_cvt_f64_f32_e32 v[4:5], v17
	v_frexp_exp_i32_f64_e32 v4, v[4:5]
	v_cmp_gt_f32_e32 vcc, s10, v19
	s_nop 1
	v_subbrev_co_u32_e32 v30, vcc, 0, v4, vcc
	v_sub_u32_e32 v4, 0, v30
	v_ldexp_f32 v5, v17, v4
	v_add_f32_e32 v17, -1.0, v5
	v_add_f32_e32 v19, 1.0, v5
	v_ldexp_f32 v4, v18, v4
	v_add_f32_e32 v18, 1.0, v17
	v_add_f32_e32 v20, -1.0, v19
	v_sub_f32_e32 v18, v5, v18
	v_sub_f32_e32 v5, v5, v20
	v_add_f32_e32 v18, v4, v18
	v_add_f32_e32 v4, v4, v5
	v_add_f32_e32 v31, v19, v4
	v_rcp_f32_e32 v33, v31
	v_sub_f32_e32 v5, v31, v19
	v_sub_f32_e32 v32, v4, v5
	v_add_f32_e32 v5, v17, v18
	v_sub_f32_e32 v4, v5, v17
	v_mul_f32_e32 v34, v5, v33
	v_sub_f32_e32 v17, v18, v4
	v_mul_f32_e32 v18, v31, v34
	v_fma_f32 v20, v34, v31, -v18
	v_fmac_f32_e32 v20, v34, v32
	v_add_f32_e32 v4, v18, v20
	v_sub_f32_e32 v19, v5, v4
	v_pk_add_f32 v[28:29], v[4:5], v[18:19] neg_lo:[0,1] neg_hi:[0,1]
	v_mov_b32_e32 v21, v4
	v_pk_add_f32 v[4:5], v[28:29], v[20:21] neg_lo:[0,1] neg_hi:[0,1]
	v_cmp_neq_f32_e32 vcc, s12, v13
	v_add_f32_e32 v5, v17, v5
	v_add_f32_e32 v4, v4, v5
	v_add_f32_e32 v5, v19, v4
	v_mul_f32_e32 v17, v33, v5
	v_mul_f32_e32 v18, v31, v17
	v_fma_f32 v20, v17, v31, -v18
	v_fmac_f32_e32 v20, v17, v32
	v_sub_f32_e32 v19, v19, v5
	v_add_f32_e32 v31, v4, v19
	v_add_f32_e32 v4, v18, v20
	v_sub_f32_e32 v19, v5, v4
	v_pk_add_f32 v[28:29], v[4:5], v[18:19] neg_lo:[0,1] neg_hi:[0,1]
	v_mov_b32_e32 v21, v4
	v_pk_add_f32 v[4:5], v[28:29], v[20:21] neg_lo:[0,1] neg_hi:[0,1]
	s_nop 0
	v_add_f32_e32 v5, v31, v5
	v_add_f32_e32 v4, v4, v5
	v_add_f32_e32 v5, v34, v17
	v_add_f32_e32 v4, v19, v4
	v_sub_f32_e32 v18, v5, v34
	v_mul_f32_e32 v4, v33, v4
	v_sub_f32_e32 v17, v17, v18
	v_add_f32_e32 v18, v17, v4
	v_add_f32_e32 v20, v5, v18
	v_mul_f32_e32 v21, v20, v20
	v_fmamk_f32 v4, v21, 0x3e9b6dac, v23
	v_fmaak_f32 v17, v21, v4, 0x3f2aaada
	v_cvt_f32_i32_e32 v4, v30
	v_sub_f32_e32 v5, v20, v5
	v_sub_f32_e32 v5, v18, v5
	v_ldexp_f32 v28, v5, 1
	v_mul_f32_e32 v5, v20, v21
	v_ldexp_f32 v19, v20, 1
	v_pk_mul_f32 v[20:21], v[4:5], v[16:17]
	s_nop 0
	v_fma_f32 v18, v4, s11, -v20
	v_fmac_f32_e32 v18, 0xb102e308, v4
	v_pk_add_f32 v[4:5], v[20:21], v[18:19]
	s_nop 0
	v_sub_f32_e32 v17, v5, v19
	v_sub_f32_e32 v17, v21, v17
	v_add_f32_e32 v29, v28, v17
	v_mov_b32_e32 v28, v20
	v_pk_add_f32 v[20:21], v[4:5], v[20:21] neg_lo:[0,1] neg_hi:[0,1]
	v_pk_add_f32 v[30:31], v[4:5], v[28:29]
	v_mov_b32_e32 v19, v4
	v_mov_b32_e32 v21, v31
	v_pk_add_f32 v[32:33], v[18:19], v[20:21] neg_lo:[0,1] neg_hi:[0,1]
	v_pk_add_f32 v[18:19], v[18:19], v[20:21]
	v_mov_b32_e32 v28, v29
	v_pk_add_f32 v[20:21], v[18:19], v[4:5] op_sel:[1,0] op_sel_hi:[0,1] neg_lo:[0,1] neg_hi:[0,1]
	v_pk_add_f32 v[34:35], v[30:31], v[20:21] op_sel_hi:[1,0] neg_lo:[0,1] neg_hi:[0,1]
	v_mov_b32_e32 v30, v31
	v_mov_b32_e32 v31, v19
	v_pk_mov_b32 v[20:21], v[4:5], v[20:21] op_sel:[1,0]
	v_mov_b32_e32 v29, v4
	v_pk_add_f32 v[20:21], v[30:31], v[20:21] neg_lo:[0,1] neg_hi:[0,1]
	v_mov_b32_e32 v34, v32
	v_pk_add_f32 v[4:5], v[28:29], v[20:21] neg_lo:[0,1] neg_hi:[0,1]
	v_mov_b32_e32 v33, v19
	v_pk_add_f32 v[20:21], v[34:35], v[4:5]
	s_nop 0
	v_pk_add_f32 v[28:29], v[20:21], v[20:21] op_sel:[0,1] op_sel_hi:[1,0]
	s_nop 0
	v_pk_add_f32 v[18:19], v[18:19], v[28:29] op_sel:[1,0] op_sel_hi:[0,1]
	v_mov_b32_e32 v21, v18
	v_pk_add_f32 v[30:31], v[20:21], v[32:33] neg_lo:[0,1] neg_hi:[0,1]
	v_mov_b32_e32 v5, v28
	v_sub_f32_e32 v17, v20, v30
	v_pk_add_f32 v[4:5], v[4:5], v[30:31] neg_lo:[0,1] neg_hi:[0,1]
	v_sub_f32_e32 v17, v32, v17
	v_add_f32_e32 v4, v4, v17
	v_add_f32_e32 v4, v4, v5
	v_add_f32_e32 v4, v18, v4
	v_cndmask_b32_e32 v4, v24, v4, vcc
	v_cmp_ngt_f32_e32 vcc, -1.0, v13
	s_nop 1
	v_cndmask_b32_e32 v4, v25, v4, vcc
	v_cmp_neq_f32_e32 vcc, -1.0, v13
	s_nop 1
	v_cndmask_b32_e32 v4, v26, v4, vcc
	v_cmp_lt_f32_e64 vcc, |v13|, s13
	s_nop 1
	v_cndmask_b32_e32 v4, v4, v13, vcc
	v_sub_f32_e32 v4, v27, v4
	s_branch .LBB0_440
